# GEMM1 phase start staggered: WGs with bx&4 sleep ~4us after seam 0 (de-synchronise the per-round epilogue store bursts of the two XCD halves); on top of v065
# speedup vs baseline: 1.0015x; 1.0015x over previous
; #define REP(k) for (int rep_ = 0; rep_ < (((REPMASK >> (k)) & 1) ? 2 : 1); ++rep_)
; #define fresh_tid() ((wave0 << 6) | lane_id_fresh())
; #define SEAM(k) do { if constexpr (COOP) { if (IN(k) && IN((k) + 1)) { if ((k) == CG_SEAM) cg::this_grid().sync(); else xcd_barrier(xbar, xst, lane_id_fresh() == 0 && wave0 == 0); } } } while (0)
;     __device__ bool next(int i, Unit& u) const {
;     ...
;         const long L = (long)ti * G + c; if (L >= nwg) return false;
;         int wgid = (int)L; { const int q = nwg / NXCD, r = nwg % NXCD, xcd = wgid % NXCD, off = wgid / NXCD; wgid = (xcd < r ? xcd * (q + 1) : r * (q + 1) + (xcd - r) * q) + off; }
;         const int nig = wgm * nN, gid = wgid / nig, fm = gid * wgm, gsz = (nM - fm) < wgm ? (nM - fm) : wgm;
;         u.pm = fm + ((wgid % nig) % gsz); u.pn = (wgid % nig) / gsz; return true;
; template <int COOP>
; __global__ void __launch_bounds__(512, 2) mega(Args a) {
;     ...
;     if (IN(0)) REP(0) { const Ptrs P = mkptrs(ptab); p0_prologue(P, lds, vcu, G, fresh_tid()); }
;     SEAM(0);
;     if (IN(1)) REP(1) { const Ptrs P = mkptrs(ptab);
;     ...
;         { pg8::Gemm g{P.U, P.W1T, T, 16384, D, D}; pg8::StaticOrder S; S.init(T, 16384, G, bx);
;           pg8::EpiG1 E{P.PA, P.PP, P.PGG};
;           pg8::gemm_phase<pg8::EpiG1, pg8::StaticOrder, false>(lds, g, S, E, fresh_tid()); }
.Lsx0_217:
	s_or_b64 exec, exec, s[0:1]
	s_cmpk_lt_i32 s2, 0x800
	s_cselect_b64 s[0:1], -1, 0
	s_ashr_i32 s3, s2, 31
	s_lshr_b32 s4, s3, 29
	s_add_i32 s4, s2, s4
	s_ashr_i32 s64, s4, 3
	s_and_b32 s4, s4, -8
	s_sub_i32 s65, s2, s4
	s_cmp_lt_i32 s65, 0
	s_cselect_b64 s[40:41], -1, 0
	s_cmp_gt_i32 s65, -1
	s_cselect_b64 s[38:39], -1, 0
	s_add_i32 s4, 0, 0x24040
	v_mov_b32_e32 v0, s4
	s_add_i32 s4, 0, 0x24060
	s_barrier
	s_bitcmp1_b32 s2, 2
	s_cbranch_scc0 .Lstg1_skip
	s_sleep 127
.Lstg1_skip:
	ds_read_b64 v[0:1], v0
	v_mov_b32_e32 v2, s4
	ds_read_b64 v[2:3], v2
	v_mbcnt_lo_u32_b32 v8, -1, 0
	v_mbcnt_hi_u32_b32 v8, -1, v8
	s_and_b64 vcc, exec, s[0:1]
	s_waitcnt lgkmcnt(1)
	v_readfirstlane_b32 s8, v0
	v_or_b32_e32 v0, s33, v8
	v_readfirstlane_b32 s9, v1
	s_waitcnt lgkmcnt(0)
	v_readfirstlane_b32 s7, v3
	v_readfirstlane_b32 s53, v2
	v_readfirstlane_b32 s16, v0
	s_cbranch_vccz .LBB0_88
	s_lshl_b32 s11, s65, 8
	s_mul_i32 s10, s65, 0x101
	s_and_b64 s[4:5], s[40:41], exec
	s_cselect_b32 s4, s10, s11
	s_add_i32 s4, s4, s64
	s_ashr_i32 s5, s4, 31
	s_lshr_b32 s5, s5, 23
	s_add_i32 s5, s4, s5
	s_ashr_i32 s10, s5, 9
	s_and_b32 s5, s5, 0xfe00
	s_sub_i32 s4, s4, s5
	s_sext_i32_i16 s5, s4
	s_bfe_u32 s5, s5, 0x3001c
	s_add_i32 s5, s4, s5
	s_sext_i32_i16 s11, s5
	s_and_b32 s5, s5, 0xfff8
	s_sub_i32 s4, s4, s5
	s_lshl_b32 s10, s10, 3
	s_sext_i32_i16 s4, s4
	s_add_i32 s4, s10, s4
	s_ashr_i32 s18, s11, 3
